# v62 + P1 rope epilogue: rotary-table rows of groups 1..7 fetched once at the top, 14 reload+vmcnt(0) store drains replaced by register copies
# speedup vs baseline: 1.0193x; 1.0131x over previous
.LBB0_306:
	s_andn2_b64 vcc, exec, s[0:1]
	s_cbranch_vccnz .LBB0_466
	v_lshlrev_b32_e32 v130, 5, v152
	v_cmp_gt_i32_e64 s[8:9], s39, v152
	v_and_b32_e32 v130, 0xf9e0, v130
	s_cmp_lt_u32 s86, 18
	v_cndmask_b32_e64 v130, v172, v130, s[8:9]
	v_or_b32_e32 v130, v130, v165
	v_lshlrev_b32_e32 v158, 3, v130
	global_load_dwordx4 v[176:179], v158, s[44:45] offset:16
	global_load_dwordx4 v[130:133], v158, s[44:45]
	v_or_b32_e32 v241, 16, v152
	v_cmp_gt_i32_e32 vcc, s39, v241
	v_lshlrev_b32_e32 v240, 5, v241
	v_and_b32_e32 v240, 0xfbe0, v240
	s_nop 0
	v_cndmask_b32_e32 v240, v172, v240, vcc
	v_or_b32_e32 v240, v240, v165
	v_lshlrev_b32_e32 v240, 3, v240
	global_load_dwordx4 v[184:187], v240, s[44:45] offset:16
	global_load_dwordx4 v[188:191], v240, s[44:45]
	v_or_b32_e32 v241, 32, v152
	v_cmp_gt_i32_e32 vcc, s39, v241
	v_lshlrev_b32_e32 v240, 5, v241
	v_and_b32_e32 v240, 0xfde0, v240
	s_nop 0
	v_cndmask_b32_e32 v240, v172, v240, vcc
	v_or_b32_e32 v240, v240, v165
	v_lshlrev_b32_e32 v240, 3, v240
	global_load_dwordx4 v[192:195], v240, s[44:45] offset:16
	global_load_dwordx4 v[196:199], v240, s[44:45]
	v_or_b32_e32 v241, 48, v152
	v_cmp_gt_i32_e32 vcc, s39, v241
	v_lshlrev_b32_e32 v240, 5, v241
	v_and_b32_e32 v240, 0xffe0, v240
	s_nop 0
	v_cndmask_b32_e32 v240, v172, v240, vcc
	v_or_b32_e32 v240, v240, v165
	v_lshlrev_b32_e32 v240, 3, v240
	global_load_dwordx4 v[200:203], v240, s[44:45] offset:16
	global_load_dwordx4 v[204:207], v240, s[44:45]
	v_add_u32_e32 v241, 0x80, v152
	v_cmp_gt_i32_e32 vcc, s39, v241
	v_lshlrev_b32_e32 v240, 5, v241
	v_and_b32_e32 v240, 0xf9e0, v240
	s_nop 0
	v_cndmask_b32_e32 v240, v172, v240, vcc
	v_or_b32_e32 v240, v240, v165
	v_lshlrev_b32_e32 v240, 3, v240
	global_load_dwordx4 v[208:211], v240, s[44:45] offset:16
	global_load_dwordx4 v[212:215], v240, s[44:45]
	v_add_u32_e32 v241, 0x90, v152
	v_cmp_gt_i32_e32 vcc, s39, v241
	v_lshlrev_b32_e32 v240, 5, v241
	v_and_b32_e32 v240, 0xfbe0, v240
	s_nop 0
	v_cndmask_b32_e32 v240, v172, v240, vcc
	v_or_b32_e32 v240, v240, v165
	v_lshlrev_b32_e32 v240, 3, v240
	global_load_dwordx4 v[216:219], v240, s[44:45] offset:16
	global_load_dwordx4 v[220:223], v240, s[44:45]
	v_add_u32_e32 v241, 0xa0, v152
	v_cmp_gt_i32_e32 vcc, s39, v241
	v_lshlrev_b32_e32 v240, 5, v241
	v_and_b32_e32 v240, 0xfde0, v240
	s_nop 0
	v_cndmask_b32_e32 v240, v172, v240, vcc
	v_or_b32_e32 v240, v240, v165
	v_lshlrev_b32_e32 v240, 3, v240
	global_load_dwordx4 v[224:227], v240, s[44:45] offset:16
	global_load_dwordx4 v[228:231], v240, s[44:45]
	v_add_u32_e32 v241, 0xb0, v152
	v_cmp_gt_i32_e32 vcc, s39, v241
	v_lshlrev_b32_e32 v240, 5, v241
	v_and_b32_e32 v240, 0xffe0, v240
	s_nop 0
	v_cndmask_b32_e32 v240, v172, v240, vcc
	v_or_b32_e32 v240, v240, v165
	v_lshlrev_b32_e32 v240, 3, v240
	global_load_dwordx4 v[232:235], v240, s[44:45] offset:16
	global_load_dwordx4 v[236:239], v240, s[44:45]
	s_cselect_b64 s[0:1], -1, 0
	s_cmp_gt_u32 s86, 17
	s_cselect_b64 s[10:11], -1, 0
	s_lshl_b32 s4, s86, 8
	s_or_b32 s4, s4, s14
	v_add_u32_e32 v146, 0xffffc000, v152
	v_ashrrev_i32_e32 v153, 31, v152
	s_and_b32 s4, s4, 0x140
	v_cmp_gt_i32_e64 s[6:7], s87, v152
	v_lshlrev_b64 v[154:155], 11, v[146:147]
	v_lshlrev_b64 v[156:157], 11, v[152:153]
	s_and_b64 vcc, exec, s[10:11]
	s_waitcnt vmcnt(0)
	v_mov_b32_e32 v137, v132
	v_mov_b32_e32 v132, v131
	v_mov_b32_e32 v136, v130
	v_pk_mul_f32 v[130:131], v[122:123], v[132:133]
	s_nop 0
	v_pk_fma_f32 v[134:135], v[126:127], v[136:137], v[130:131] neg_lo:[0,0,1] neg_hi:[0,0,1]
	v_pk_mul_f32 v[130:131], v[122:123], v[136:137]
	s_nop 0
	v_pk_fma_f32 v[130:131], v[126:127], v[132:133], v[130:131]
	v_mov_b32_e32 v133, v178
	v_mov_b32_e32 v178, v177
	v_mov_b32_e32 v132, v176
	v_pk_mul_f32 v[136:137], v[124:125], v[178:179]
	v_or_b32_e32 v176, s4, v165
	v_pk_fma_f32 v[136:137], v[128:129], v[132:133], v[136:137] neg_lo:[0,0,1] neg_hi:[0,0,1]
	v_pk_mul_f32 v[132:133], v[124:125], v[132:133]
	s_mov_b64 s[4:5], -1
	v_pk_fma_f32 v[132:133], v[128:129], v[178:179], v[132:133]
	s_cbranch_vccz .LBB0_311
	s_and_saveexec_b64 s[4:5], s[6:7]
	s_cbranch_execz .LBB0_310
	v_readlane_b32 s48, v245, 25
	v_cndmask_b32_e64 v146, v173, v174, s[8:9]
	v_readlane_b32 s62, v245, 39
	v_readlane_b32 s63, v245, 40
	v_cndmask_b32_e64 v179, v155, v157, s[8:9]
	v_cndmask_b32_e64 v178, v154, v156, s[8:9]
	v_lshl_add_u64 v[160:161], s[62:63], 0, v[146:147]
	v_lshl_add_u64 v[160:161], v[160:161], 0, v[178:179]
	v_lshlrev_b32_e32 v146, 2, v176
	v_lshl_add_u64 v[160:161], v[160:161], 0, v[146:147]
	v_readlane_b32 s49, v245, 26
	v_readlane_b32 s50, v245, 27
	v_readlane_b32 s51, v245, 28
	v_readlane_b32 s52, v245, 29
	v_readlane_b32 s53, v245, 30
	v_readlane_b32 s54, v245, 31
	v_readlane_b32 s55, v245, 32
	v_readlane_b32 s56, v245, 33
	v_readlane_b32 s57, v245, 34
	v_readlane_b32 s58, v245, 35
	v_readlane_b32 s59, v245, 36
	v_readlane_b32 s60, v245, 37
	v_readlane_b32 s61, v245, 38
	global_store_dwordx4 v[160:161], v[134:137], off
	global_store_dwordx4 v[160:161], v[130:133], off offset:128

.LBB0_327:
	v_or_b32_e32 v160, 16, v152
	v_lshlrev_b32_e32 v130, 5, v160
	v_cmp_gt_i32_e64 s[10:11], s39, v160
	v_and_b32_e32 v130, 0xfbe0, v130
	v_mov_b32_e32 v131, v147
	v_cndmask_b32_e64 v130, v172, v130, s[10:11]
	v_or_b32_e32 v130, v130, v165
	v_lshlrev_b32_e32 v158, 3, v130
	v_add_u32_e32 v130, 0xffffc010, v152
	v_lshlrev_b64 v[154:155], 11, v[130:131]
	v_mov_b32_e32 v178, v184
	v_mov_b32_e32 v179, v185
	v_mov_b32_e32 v180, v186
	v_mov_b32_e32 v181, v187
	v_mov_b32_e32 v130, v188
	v_mov_b32_e32 v131, v189
	v_mov_b32_e32 v132, v190
	v_mov_b32_e32 v133, v191
	v_ashrrev_i32_e32 v161, 31, v160
	v_cmp_gt_i32_e64 s[12:13], s87, v160
	v_lshlrev_b64 v[156:157], 11, v[160:161]
	s_mov_b64 s[24:25], -1
	s_and_b64 vcc, exec, s[4:5]
	v_mov_b32_e32 v137, v132
	v_mov_b32_e32 v132, v131
	v_mov_b32_e32 v136, v130
	v_pk_mul_f32 v[130:131], v[106:107], v[132:133]
	s_nop 0
	v_pk_fma_f32 v[134:135], v[114:115], v[136:137], v[130:131] neg_lo:[0,0,1] neg_hi:[0,0,1]
	v_pk_mul_f32 v[130:131], v[106:107], v[136:137]
	s_nop 0
	v_pk_fma_f32 v[130:131], v[114:115], v[132:133], v[130:131]
	v_mov_b32_e32 v133, v180
	v_mov_b32_e32 v180, v179
	v_mov_b32_e32 v132, v178
	v_pk_mul_f32 v[136:137], v[108:109], v[180:181]
	s_nop 0
	v_pk_fma_f32 v[136:137], v[116:117], v[132:133], v[136:137] neg_lo:[0,0,1] neg_hi:[0,0,1]
	v_pk_mul_f32 v[132:133], v[108:109], v[132:133]
	s_nop 0
	v_pk_fma_f32 v[132:133], v[116:117], v[180:181], v[132:133]
	s_cbranch_vccnz .LBB0_331
	s_and_saveexec_b64 s[24:25], s[12:13]
	s_cbranch_execz .LBB0_330
	v_readlane_b32 s48, v245, 25
	v_cndmask_b32_e64 v178, v173, v174, s[10:11]
	v_mov_b32_e32 v179, v147
	v_readlane_b32 s62, v245, 39
	v_readlane_b32 s63, v245, 40
	v_cndmask_b32_e64 v181, v155, v157, s[10:11]
	v_cndmask_b32_e64 v180, v154, v156, s[10:11]
	v_lshl_add_u64 v[178:179], s[62:63], 0, v[178:179]
	v_lshl_add_u64 v[178:179], v[178:179], 0, v[180:181]
	v_lshlrev_b32_e32 v180, 2, v176
	v_mov_b32_e32 v181, v147
	v_lshl_add_u64 v[178:179], v[178:179], 0, v[180:181]
	v_readlane_b32 s49, v245, 26
	v_readlane_b32 s50, v245, 27
	v_readlane_b32 s51, v245, 28
	v_readlane_b32 s52, v245, 29
	v_readlane_b32 s53, v245, 30
	v_readlane_b32 s54, v245, 31
	v_readlane_b32 s55, v245, 32
	v_readlane_b32 s56, v245, 33
	v_readlane_b32 s57, v245, 34
	v_readlane_b32 s58, v245, 35
	v_readlane_b32 s59, v245, 36
	v_readlane_b32 s60, v245, 37
	v_readlane_b32 s61, v245, 38
	global_store_dwordx4 v[178:179], v[134:137], off
	global_store_dwordx4 v[178:179], v[130:133], off offset:128

.LBB0_337:
	v_mov_b32_e32 v159, v147
	v_lshl_add_u64 v[130:131], s[44:45], 0, v[158:159]
	v_mov_b32_e32 v178, v184
	v_mov_b32_e32 v179, v185
	v_mov_b32_e32 v180, v186
	v_mov_b32_e32 v181, v187
	s_nop 0
	v_mov_b32_e32 v130, v188
	v_mov_b32_e32 v131, v189
	v_mov_b32_e32 v132, v190
	v_mov_b32_e32 v133, v191
	s_mov_b64 s[24:25], -1
	s_and_b64 vcc, exec, s[4:5]
	v_mov_b32_e32 v137, v132
	v_mov_b32_e32 v132, v131
	v_mov_b32_e32 v136, v130
	v_pk_mul_f32 v[130:131], v[94:95], v[132:133]
	s_nop 0
	v_pk_fma_f32 v[134:135], v[102:103], v[136:137], v[130:131] neg_lo:[0,0,1] neg_hi:[0,0,1]
	v_pk_mul_f32 v[130:131], v[94:95], v[136:137]
	s_nop 0
	v_pk_fma_f32 v[130:131], v[102:103], v[132:133], v[130:131]
	v_mov_b32_e32 v133, v180
	v_mov_b32_e32 v180, v179
	v_mov_b32_e32 v132, v178
	v_pk_mul_f32 v[136:137], v[96:97], v[180:181]
	s_nop 0
	v_pk_fma_f32 v[136:137], v[104:105], v[132:133], v[136:137] neg_lo:[0,0,1] neg_hi:[0,0,1]
	v_pk_mul_f32 v[132:133], v[96:97], v[132:133]
	s_nop 0
	v_pk_fma_f32 v[132:133], v[104:105], v[180:181], v[132:133]
	s_cbranch_vccnz .LBB0_341
	s_and_saveexec_b64 s[24:25], s[12:13]
	s_cbranch_execz .LBB0_340
	v_readlane_b32 s48, v245, 25
	v_cndmask_b32_e64 v158, v173, v174, s[10:11]
	v_mov_b32_e32 v159, v147
	v_readlane_b32 s62, v245, 39
	v_readlane_b32 s63, v245, 40
	v_cndmask_b32_e64 v155, v155, v157, s[10:11]
	v_cndmask_b32_e64 v154, v154, v156, s[10:11]
	v_lshl_add_u64 v[158:159], s[62:63], 0, v[158:159]
	v_lshl_add_u64 v[154:155], v[158:159], 0, v[154:155]
	v_lshlrev_b32_e32 v156, 2, v176
	v_mov_b32_e32 v157, v147
	v_lshl_add_u64 v[154:155], v[154:155], 0, v[156:157]
	v_readlane_b32 s49, v245, 26
	v_readlane_b32 s50, v245, 27
	v_readlane_b32 s51, v245, 28
	v_readlane_b32 s52, v245, 29
	v_readlane_b32 s53, v245, 30
	v_readlane_b32 s54, v245, 31
	v_readlane_b32 s55, v245, 32
	v_readlane_b32 s56, v245, 33
	v_readlane_b32 s57, v245, 34
	v_readlane_b32 s58, v245, 35
	v_readlane_b32 s59, v245, 36
	v_readlane_b32 s60, v245, 37
	v_readlane_b32 s61, v245, 38
	global_store_dwordx4 v[154:155], v[134:137], off offset:512
	global_store_dwordx4 v[154:155], v[130:133], off offset:640

.LBB0_347:
	v_or_b32_e32 v160, 32, v152
	v_lshlrev_b32_e32 v130, 5, v160
	v_cmp_gt_i32_e64 s[10:11], s39, v160
	v_and_b32_e32 v130, 0xfde0, v130
	v_mov_b32_e32 v131, v147
	v_cndmask_b32_e64 v130, v172, v130, s[10:11]
	v_or_b32_e32 v130, v130, v165
	v_lshlrev_b32_e32 v158, 3, v130
	v_add_u32_e32 v130, 0xffffc020, v152
	v_lshlrev_b64 v[154:155], 11, v[130:131]
	v_mov_b32_e32 v178, v192
	v_mov_b32_e32 v179, v193
	v_mov_b32_e32 v180, v194
	v_mov_b32_e32 v181, v195
	v_mov_b32_e32 v130, v196
	v_mov_b32_e32 v131, v197
	v_mov_b32_e32 v132, v198
	v_mov_b32_e32 v133, v199
	v_ashrrev_i32_e32 v161, 31, v160
	v_cmp_gt_i32_e64 s[12:13], s87, v160
	v_lshlrev_b64 v[156:157], 11, v[160:161]
	s_mov_b64 s[24:25], -1
	s_and_b64 vcc, exec, s[4:5]
	v_mov_b32_e32 v137, v132
	v_mov_b32_e32 v132, v131
	v_mov_b32_e32 v136, v130
	v_pk_mul_f32 v[130:131], v[90:91], v[132:133]
	s_nop 0
	v_pk_fma_f32 v[134:135], v[98:99], v[136:137], v[130:131] neg_lo:[0,0,1] neg_hi:[0,0,1]
	v_pk_mul_f32 v[130:131], v[90:91], v[136:137]
	s_nop 0
	v_pk_fma_f32 v[130:131], v[98:99], v[132:133], v[130:131]
	v_mov_b32_e32 v133, v180
	v_mov_b32_e32 v180, v179
	v_mov_b32_e32 v132, v178
	v_pk_mul_f32 v[136:137], v[92:93], v[180:181]
	s_nop 0
	v_pk_fma_f32 v[136:137], v[100:101], v[132:133], v[136:137] neg_lo:[0,0,1] neg_hi:[0,0,1]
	v_pk_mul_f32 v[132:133], v[92:93], v[132:133]
	s_nop 0
	v_pk_fma_f32 v[132:133], v[100:101], v[180:181], v[132:133]
	s_cbranch_vccnz .LBB0_351
	s_and_saveexec_b64 s[24:25], s[12:13]
	s_cbranch_execz .LBB0_350
	v_readlane_b32 s48, v245, 25
	v_cndmask_b32_e64 v178, v173, v174, s[10:11]
	v_mov_b32_e32 v179, v147
	v_readlane_b32 s62, v245, 39
	v_readlane_b32 s63, v245, 40
	v_cndmask_b32_e64 v181, v155, v157, s[10:11]
	v_cndmask_b32_e64 v180, v154, v156, s[10:11]
	v_lshl_add_u64 v[178:179], s[62:63], 0, v[178:179]
	v_lshl_add_u64 v[178:179], v[178:179], 0, v[180:181]
	v_lshlrev_b32_e32 v180, 2, v176
	v_mov_b32_e32 v181, v147
	v_lshl_add_u64 v[178:179], v[178:179], 0, v[180:181]
	v_readlane_b32 s49, v245, 26
	v_readlane_b32 s50, v245, 27
	v_readlane_b32 s51, v245, 28
	v_readlane_b32 s52, v245, 29
	v_readlane_b32 s53, v245, 30
	v_readlane_b32 s54, v245, 31
	v_readlane_b32 s55, v245, 32
	v_readlane_b32 s56, v245, 33
	v_readlane_b32 s57, v245, 34
	v_readlane_b32 s58, v245, 35
	v_readlane_b32 s59, v245, 36
	v_readlane_b32 s60, v245, 37
	v_readlane_b32 s61, v245, 38
	global_store_dwordx4 v[178:179], v[134:137], off
	global_store_dwordx4 v[178:179], v[130:133], off offset:128

.LBB0_357:
	v_mov_b32_e32 v159, v147
	v_lshl_add_u64 v[130:131], s[44:45], 0, v[158:159]
	v_mov_b32_e32 v178, v192
	v_mov_b32_e32 v179, v193
	v_mov_b32_e32 v180, v194
	v_mov_b32_e32 v181, v195
	s_nop 0
	v_mov_b32_e32 v130, v196
	v_mov_b32_e32 v131, v197
	v_mov_b32_e32 v132, v198
	v_mov_b32_e32 v133, v199
	s_mov_b64 s[24:25], -1
	s_and_b64 vcc, exec, s[4:5]
	v_mov_b32_e32 v137, v132
	v_mov_b32_e32 v132, v131
	v_mov_b32_e32 v136, v130
	v_pk_mul_f32 v[130:131], v[78:79], v[132:133]
	s_nop 0
	v_pk_fma_f32 v[134:135], v[86:87], v[136:137], v[130:131] neg_lo:[0,0,1] neg_hi:[0,0,1]
	v_pk_mul_f32 v[130:131], v[78:79], v[136:137]
	s_nop 0
	v_pk_fma_f32 v[130:131], v[86:87], v[132:133], v[130:131]
	v_mov_b32_e32 v133, v180
	v_mov_b32_e32 v180, v179
	v_mov_b32_e32 v132, v178
	v_pk_mul_f32 v[136:137], v[80:81], v[180:181]
	s_nop 0
	v_pk_fma_f32 v[136:137], v[88:89], v[132:133], v[136:137] neg_lo:[0,0,1] neg_hi:[0,0,1]
	v_pk_mul_f32 v[132:133], v[80:81], v[132:133]
	s_nop 0
	v_pk_fma_f32 v[132:133], v[88:89], v[180:181], v[132:133]
	s_cbranch_vccnz .LBB0_361
	s_and_saveexec_b64 s[24:25], s[12:13]
	s_cbranch_execz .LBB0_360
	v_readlane_b32 s48, v245, 25
	v_cndmask_b32_e64 v158, v173, v174, s[10:11]
	v_mov_b32_e32 v159, v147
	v_readlane_b32 s62, v245, 39
	v_readlane_b32 s63, v245, 40
	v_cndmask_b32_e64 v155, v155, v157, s[10:11]
	v_cndmask_b32_e64 v154, v154, v156, s[10:11]
	v_lshl_add_u64 v[158:159], s[62:63], 0, v[158:159]
	v_lshl_add_u64 v[154:155], v[158:159], 0, v[154:155]
	v_lshlrev_b32_e32 v156, 2, v176
	v_mov_b32_e32 v157, v147
	v_lshl_add_u64 v[154:155], v[154:155], 0, v[156:157]
	v_readlane_b32 s49, v245, 26
	v_readlane_b32 s50, v245, 27
	v_readlane_b32 s51, v245, 28
	v_readlane_b32 s52, v245, 29
	v_readlane_b32 s53, v245, 30
	v_readlane_b32 s54, v245, 31
	v_readlane_b32 s55, v245, 32
	v_readlane_b32 s56, v245, 33
	v_readlane_b32 s57, v245, 34
	v_readlane_b32 s58, v245, 35
	v_readlane_b32 s59, v245, 36
	v_readlane_b32 s60, v245, 37
	v_readlane_b32 s61, v245, 38
	global_store_dwordx4 v[154:155], v[134:137], off offset:512
	global_store_dwordx4 v[154:155], v[130:133], off offset:640

.LBB0_367:
	v_or_b32_e32 v160, 48, v152
	v_lshlrev_b32_e32 v130, 5, v160
	v_cmp_gt_i32_e64 s[10:11], s39, v160
	v_and_b32_e32 v130, 0xffe0, v130
	v_mov_b32_e32 v131, v147
	v_cndmask_b32_e64 v130, v172, v130, s[10:11]
	v_or_b32_e32 v130, v130, v165
	v_lshlrev_b32_e32 v158, 3, v130
	v_add_u32_e32 v130, 0xffffc030, v152
	v_lshlrev_b64 v[154:155], 11, v[130:131]
	v_mov_b32_e32 v178, v200
	v_mov_b32_e32 v179, v201
	v_mov_b32_e32 v180, v202
	v_mov_b32_e32 v181, v203
	v_mov_b32_e32 v130, v204
	v_mov_b32_e32 v131, v205
	v_mov_b32_e32 v132, v206
	v_mov_b32_e32 v133, v207
	v_ashrrev_i32_e32 v161, 31, v160
	v_cmp_gt_i32_e64 s[12:13], s87, v160
	v_lshlrev_b64 v[156:157], 11, v[160:161]
	s_mov_b64 s[24:25], -1
	s_and_b64 vcc, exec, s[4:5]
	v_mov_b32_e32 v137, v132
	v_mov_b32_e32 v132, v131
	v_mov_b32_e32 v136, v130
	v_pk_mul_f32 v[130:131], v[74:75], v[132:133]
	s_nop 0
	v_pk_fma_f32 v[134:135], v[82:83], v[136:137], v[130:131] neg_lo:[0,0,1] neg_hi:[0,0,1]
	v_pk_mul_f32 v[130:131], v[74:75], v[136:137]
	s_nop 0
	v_pk_fma_f32 v[130:131], v[82:83], v[132:133], v[130:131]
	v_mov_b32_e32 v133, v180
	v_mov_b32_e32 v180, v179
	v_mov_b32_e32 v132, v178
	v_pk_mul_f32 v[136:137], v[76:77], v[180:181]
	s_nop 0
	v_pk_fma_f32 v[136:137], v[84:85], v[132:133], v[136:137] neg_lo:[0,0,1] neg_hi:[0,0,1]
	v_pk_mul_f32 v[132:133], v[76:77], v[132:133]
	s_nop 0
	v_pk_fma_f32 v[132:133], v[84:85], v[180:181], v[132:133]
	s_cbranch_vccnz .LBB0_371
	s_and_saveexec_b64 s[24:25], s[12:13]
	s_cbranch_execz .LBB0_370
	v_readlane_b32 s48, v245, 25
	v_cndmask_b32_e64 v178, v173, v174, s[10:11]
	v_mov_b32_e32 v179, v147
	v_readlane_b32 s62, v245, 39
	v_readlane_b32 s63, v245, 40
	v_cndmask_b32_e64 v181, v155, v157, s[10:11]
	v_cndmask_b32_e64 v180, v154, v156, s[10:11]
	v_lshl_add_u64 v[178:179], s[62:63], 0, v[178:179]
	v_lshl_add_u64 v[178:179], v[178:179], 0, v[180:181]
	v_lshlrev_b32_e32 v180, 2, v176
	v_mov_b32_e32 v181, v147
	v_lshl_add_u64 v[178:179], v[178:179], 0, v[180:181]
	v_readlane_b32 s49, v245, 26
	v_readlane_b32 s50, v245, 27
	v_readlane_b32 s51, v245, 28
	v_readlane_b32 s52, v245, 29
	v_readlane_b32 s53, v245, 30
	v_readlane_b32 s54, v245, 31
	v_readlane_b32 s55, v245, 32
	v_readlane_b32 s56, v245, 33
	v_readlane_b32 s57, v245, 34
	v_readlane_b32 s58, v245, 35
	v_readlane_b32 s59, v245, 36
	v_readlane_b32 s60, v245, 37
	v_readlane_b32 s61, v245, 38
	global_store_dwordx4 v[178:179], v[134:137], off
	global_store_dwordx4 v[178:179], v[130:133], off offset:128

.LBB0_377:
	v_mov_b32_e32 v159, v147
	v_lshl_add_u64 v[130:131], s[44:45], 0, v[158:159]
	v_mov_b32_e32 v178, v200
	v_mov_b32_e32 v179, v201
	v_mov_b32_e32 v180, v202
	v_mov_b32_e32 v181, v203
	s_nop 0
	v_mov_b32_e32 v130, v204
	v_mov_b32_e32 v131, v205
	v_mov_b32_e32 v132, v206
	v_mov_b32_e32 v133, v207
	s_mov_b64 s[24:25], -1
	s_and_b64 vcc, exec, s[4:5]
	v_mov_b32_e32 v137, v132
	v_mov_b32_e32 v132, v131
	v_mov_b32_e32 v136, v130
	v_pk_mul_f32 v[130:131], v[66:67], v[132:133]
	s_nop 0
	v_pk_fma_f32 v[134:135], v[70:71], v[136:137], v[130:131] neg_lo:[0,0,1] neg_hi:[0,0,1]
	v_pk_mul_f32 v[130:131], v[66:67], v[136:137]
	s_nop 0
	v_pk_fma_f32 v[130:131], v[70:71], v[132:133], v[130:131]
	v_mov_b32_e32 v133, v180
	v_mov_b32_e32 v180, v179
	v_mov_b32_e32 v132, v178
	v_pk_mul_f32 v[136:137], v[68:69], v[180:181]
	s_nop 0
	v_pk_fma_f32 v[136:137], v[72:73], v[132:133], v[136:137] neg_lo:[0,0,1] neg_hi:[0,0,1]
	v_pk_mul_f32 v[132:133], v[68:69], v[132:133]
	s_nop 0
	v_pk_fma_f32 v[132:133], v[72:73], v[180:181], v[132:133]
	s_cbranch_vccnz .LBB0_381
	s_and_saveexec_b64 s[24:25], s[12:13]
	s_cbranch_execz .LBB0_380
	v_readlane_b32 s48, v245, 25
	v_cndmask_b32_e64 v158, v173, v174, s[10:11]
	v_mov_b32_e32 v159, v147
	v_readlane_b32 s62, v245, 39
	v_readlane_b32 s63, v245, 40
	v_cndmask_b32_e64 v155, v155, v157, s[10:11]
	v_cndmask_b32_e64 v154, v154, v156, s[10:11]
	v_lshl_add_u64 v[158:159], s[62:63], 0, v[158:159]
	v_lshl_add_u64 v[154:155], v[158:159], 0, v[154:155]
	v_lshlrev_b32_e32 v156, 2, v176
	v_mov_b32_e32 v157, v147
	v_lshl_add_u64 v[154:155], v[154:155], 0, v[156:157]
	v_readlane_b32 s49, v245, 26
	v_readlane_b32 s50, v245, 27
	v_readlane_b32 s51, v245, 28
	v_readlane_b32 s52, v245, 29
	v_readlane_b32 s53, v245, 30
	v_readlane_b32 s54, v245, 31
	v_readlane_b32 s55, v245, 32
	v_readlane_b32 s56, v245, 33
	v_readlane_b32 s57, v245, 34
	v_readlane_b32 s58, v245, 35
	v_readlane_b32 s59, v245, 36
	v_readlane_b32 s60, v245, 37
	v_readlane_b32 s61, v245, 38
	global_store_dwordx4 v[154:155], v[134:137], off offset:512
	global_store_dwordx4 v[154:155], v[130:133], off offset:640

.LBB0_387:
	v_add_u32_e32 v160, 0x80, v152
	v_lshlrev_b32_e32 v130, 5, v160
	v_cmp_gt_i32_e64 s[10:11], s15, v152
	v_and_b32_e32 v130, 0xf9e0, v130
	v_mov_b32_e32 v131, v147
	v_cndmask_b32_e64 v130, v172, v130, s[10:11]
	v_or_b32_e32 v130, v130, v165
	v_lshlrev_b32_e32 v158, 3, v130
	v_add_u32_e32 v130, 0xffffc080, v152
	v_lshlrev_b64 v[154:155], 11, v[130:131]
	v_mov_b32_e32 v178, v208
	v_mov_b32_e32 v179, v209
	v_mov_b32_e32 v180, v210
	v_mov_b32_e32 v181, v211
	v_mov_b32_e32 v130, v212
	v_mov_b32_e32 v131, v213
	v_mov_b32_e32 v132, v214
	v_mov_b32_e32 v133, v215
	v_ashrrev_i32_e32 v161, 31, v160
	v_lshlrev_b64 v[156:157], 11, v[160:161]
	s_mov_b64 s[12:13], -1
	s_and_b64 vcc, exec, s[4:5]
	v_mov_b32_e32 v137, v132
	v_mov_b32_e32 v132, v131
	v_mov_b32_e32 v136, v130
	v_pk_mul_f32 v[130:131], v[58:59], v[132:133]
	s_nop 0
	v_pk_fma_f32 v[134:135], v[62:63], v[136:137], v[130:131] neg_lo:[0,0,1] neg_hi:[0,0,1]
	v_pk_mul_f32 v[130:131], v[58:59], v[136:137]
	s_nop 0
	v_pk_fma_f32 v[130:131], v[62:63], v[132:133], v[130:131]
	v_mov_b32_e32 v133, v180
	v_mov_b32_e32 v180, v179
	v_mov_b32_e32 v132, v178
	v_pk_mul_f32 v[136:137], v[60:61], v[180:181]
	s_nop 0
	v_pk_fma_f32 v[136:137], v[64:65], v[132:133], v[136:137] neg_lo:[0,0,1] neg_hi:[0,0,1]
	v_pk_mul_f32 v[132:133], v[60:61], v[132:133]
	s_nop 0
	v_pk_fma_f32 v[132:133], v[64:65], v[180:181], v[132:133]
	s_cbranch_vccnz .LBB0_391
	s_and_saveexec_b64 s[12:13], s[8:9]
	s_cbranch_execz .LBB0_390
	v_readlane_b32 s48, v245, 25
	v_cndmask_b32_e64 v178, v173, v174, s[10:11]
	v_mov_b32_e32 v179, v147
	v_readlane_b32 s62, v245, 39
	v_readlane_b32 s63, v245, 40
	v_cndmask_b32_e64 v181, v155, v157, s[10:11]
	v_cndmask_b32_e64 v180, v154, v156, s[10:11]
	v_lshl_add_u64 v[178:179], s[62:63], 0, v[178:179]
	v_lshl_add_u64 v[178:179], v[178:179], 0, v[180:181]
	v_lshlrev_b32_e32 v180, 2, v176
	v_mov_b32_e32 v181, v147
	v_lshl_add_u64 v[178:179], v[178:179], 0, v[180:181]
	v_readlane_b32 s49, v245, 26
	v_readlane_b32 s50, v245, 27
	v_readlane_b32 s51, v245, 28
	v_readlane_b32 s52, v245, 29
	v_readlane_b32 s53, v245, 30
	v_readlane_b32 s54, v245, 31
	v_readlane_b32 s55, v245, 32
	v_readlane_b32 s56, v245, 33
	v_readlane_b32 s57, v245, 34
	v_readlane_b32 s58, v245, 35
	v_readlane_b32 s59, v245, 36
	v_readlane_b32 s60, v245, 37
	v_readlane_b32 s61, v245, 38
	global_store_dwordx4 v[178:179], v[134:137], off
	global_store_dwordx4 v[178:179], v[130:133], off offset:128

.LBB0_397:
	v_mov_b32_e32 v159, v147
	v_lshl_add_u64 v[130:131], s[44:45], 0, v[158:159]
	v_mov_b32_e32 v178, v208
	v_mov_b32_e32 v179, v209
	v_mov_b32_e32 v180, v210
	v_mov_b32_e32 v181, v211
	s_nop 0
	v_mov_b32_e32 v130, v212
	v_mov_b32_e32 v131, v213
	v_mov_b32_e32 v132, v214
	v_mov_b32_e32 v133, v215
	s_mov_b64 s[12:13], -1
	s_and_b64 vcc, exec, s[4:5]
	v_mov_b32_e32 v137, v132
	v_mov_b32_e32 v132, v131
	v_mov_b32_e32 v136, v130
	v_pk_mul_f32 v[130:131], v[46:47], v[132:133]
	s_nop 0
	v_pk_fma_f32 v[134:135], v[54:55], v[136:137], v[130:131] neg_lo:[0,0,1] neg_hi:[0,0,1]
	v_pk_mul_f32 v[130:131], v[46:47], v[136:137]
	s_nop 0
	v_pk_fma_f32 v[130:131], v[54:55], v[132:133], v[130:131]
	v_mov_b32_e32 v133, v180
	v_mov_b32_e32 v180, v179
	v_mov_b32_e32 v132, v178
	v_pk_mul_f32 v[136:137], v[48:49], v[180:181]
	s_nop 0
	v_pk_fma_f32 v[136:137], v[56:57], v[132:133], v[136:137] neg_lo:[0,0,1] neg_hi:[0,0,1]
	v_pk_mul_f32 v[132:133], v[48:49], v[132:133]
	s_nop 0
	v_pk_fma_f32 v[132:133], v[56:57], v[180:181], v[132:133]
	s_cbranch_vccnz .LBB0_401
	s_and_saveexec_b64 s[12:13], s[8:9]
	s_cbranch_execz .LBB0_400
	v_readlane_b32 s48, v245, 25
	v_cndmask_b32_e64 v158, v173, v174, s[10:11]
	v_mov_b32_e32 v159, v147
	v_readlane_b32 s62, v245, 39
	v_readlane_b32 s63, v245, 40
	v_cndmask_b32_e64 v155, v155, v157, s[10:11]
	v_cndmask_b32_e64 v154, v154, v156, s[10:11]
	v_lshl_add_u64 v[158:159], s[62:63], 0, v[158:159]
	v_lshl_add_u64 v[154:155], v[158:159], 0, v[154:155]
	v_lshlrev_b32_e32 v156, 2, v176
	v_mov_b32_e32 v157, v147
	v_lshl_add_u64 v[154:155], v[154:155], 0, v[156:157]
	v_readlane_b32 s49, v245, 26
	v_readlane_b32 s50, v245, 27
	v_readlane_b32 s51, v245, 28
	v_readlane_b32 s52, v245, 29
	v_readlane_b32 s53, v245, 30
	v_readlane_b32 s54, v245, 31
	v_readlane_b32 s55, v245, 32
	v_readlane_b32 s56, v245, 33
	v_readlane_b32 s57, v245, 34
	v_readlane_b32 s58, v245, 35
	v_readlane_b32 s59, v245, 36
	v_readlane_b32 s60, v245, 37
	v_readlane_b32 s61, v245, 38
	global_store_dwordx4 v[154:155], v[134:137], off offset:512
	global_store_dwordx4 v[154:155], v[130:133], off offset:640

.LBB0_407:
	v_add_u32_e32 v160, 0x90, v152
	s_movk_i32 s8, 0x3f70
	v_lshlrev_b32_e32 v130, 5, v160
	v_cmp_gt_i32_e64 s[8:9], s8, v152
	v_and_b32_e32 v130, 0xfbe0, v130
	v_mov_b32_e32 v131, v147
	v_cndmask_b32_e64 v130, v172, v130, s[8:9]
	v_or_b32_e32 v130, v130, v165
	v_lshlrev_b32_e32 v158, 3, v130
	v_add_u32_e32 v130, 0xffffc090, v152
	v_lshlrev_b64 v[154:155], 11, v[130:131]
	v_mov_b32_e32 v178, v216
	v_mov_b32_e32 v179, v217
	v_mov_b32_e32 v180, v218
	v_mov_b32_e32 v181, v219
	v_mov_b32_e32 v130, v220
	v_mov_b32_e32 v131, v221
	v_mov_b32_e32 v132, v222
	v_mov_b32_e32 v133, v223
	s_movk_i32 s10, 0x3ff0
	v_ashrrev_i32_e32 v161, 31, v160
	v_cmp_gt_i32_e64 s[10:11], s10, v152
	v_lshlrev_b64 v[156:157], 11, v[160:161]
	s_mov_b64 s[12:13], -1
	s_and_b64 vcc, exec, s[4:5]
	v_mov_b32_e32 v137, v132
	v_mov_b32_e32 v132, v131
	v_mov_b32_e32 v136, v130
	v_pk_mul_f32 v[130:131], v[42:43], v[132:133]
	s_nop 0
	v_pk_fma_f32 v[134:135], v[50:51], v[136:137], v[130:131] neg_lo:[0,0,1] neg_hi:[0,0,1]
	v_pk_mul_f32 v[130:131], v[42:43], v[136:137]
	s_nop 0
	v_pk_fma_f32 v[130:131], v[50:51], v[132:133], v[130:131]
	v_mov_b32_e32 v133, v180
	v_mov_b32_e32 v180, v179
	v_mov_b32_e32 v132, v178
	v_pk_mul_f32 v[136:137], v[44:45], v[180:181]
	s_nop 0
	v_pk_fma_f32 v[136:137], v[52:53], v[132:133], v[136:137] neg_lo:[0,0,1] neg_hi:[0,0,1]
	v_pk_mul_f32 v[132:133], v[44:45], v[132:133]
	s_nop 0
	v_pk_fma_f32 v[132:133], v[52:53], v[180:181], v[132:133]
	s_cbranch_vccnz .LBB0_411
	s_and_saveexec_b64 s[12:13], s[10:11]
	s_cbranch_execz .LBB0_410
	v_readlane_b32 s48, v245, 25
	v_cndmask_b32_e64 v178, v173, v174, s[8:9]
	v_mov_b32_e32 v179, v147
	v_readlane_b32 s62, v245, 39
	v_readlane_b32 s63, v245, 40
	v_cndmask_b32_e64 v181, v155, v157, s[8:9]
	v_cndmask_b32_e64 v180, v154, v156, s[8:9]
	v_lshl_add_u64 v[178:179], s[62:63], 0, v[178:179]
	v_lshl_add_u64 v[178:179], v[178:179], 0, v[180:181]
	v_lshlrev_b32_e32 v180, 2, v176
	v_mov_b32_e32 v181, v147
	v_lshl_add_u64 v[178:179], v[178:179], 0, v[180:181]
	v_readlane_b32 s49, v245, 26
	v_readlane_b32 s50, v245, 27
	v_readlane_b32 s51, v245, 28
	v_readlane_b32 s52, v245, 29
	v_readlane_b32 s53, v245, 30
	v_readlane_b32 s54, v245, 31
	v_readlane_b32 s55, v245, 32
	v_readlane_b32 s56, v245, 33
	v_readlane_b32 s57, v245, 34
	v_readlane_b32 s58, v245, 35
	v_readlane_b32 s59, v245, 36
	v_readlane_b32 s60, v245, 37
	v_readlane_b32 s61, v245, 38
	global_store_dwordx4 v[178:179], v[134:137], off
	global_store_dwordx4 v[178:179], v[130:133], off offset:128

.LBB0_417:
	v_mov_b32_e32 v159, v147
	v_lshl_add_u64 v[130:131], s[44:45], 0, v[158:159]
	v_mov_b32_e32 v178, v216
	v_mov_b32_e32 v179, v217
	v_mov_b32_e32 v180, v218
	v_mov_b32_e32 v181, v219
	s_nop 0
	v_mov_b32_e32 v130, v220
	v_mov_b32_e32 v131, v221
	v_mov_b32_e32 v132, v222
	v_mov_b32_e32 v133, v223
	s_mov_b64 s[12:13], -1
	s_and_b64 vcc, exec, s[4:5]
	v_mov_b32_e32 v137, v132
	v_mov_b32_e32 v132, v131
	v_mov_b32_e32 v136, v130
	v_pk_mul_f32 v[130:131], v[30:31], v[132:133]
	s_nop 0
	v_pk_fma_f32 v[134:135], v[38:39], v[136:137], v[130:131] neg_lo:[0,0,1] neg_hi:[0,0,1]
	v_pk_mul_f32 v[130:131], v[30:31], v[136:137]
	s_nop 0
	v_pk_fma_f32 v[130:131], v[38:39], v[132:133], v[130:131]
	v_mov_b32_e32 v133, v180
	v_mov_b32_e32 v180, v179
	v_mov_b32_e32 v132, v178
	v_pk_mul_f32 v[136:137], v[32:33], v[180:181]
	s_nop 0
	v_pk_fma_f32 v[136:137], v[40:41], v[132:133], v[136:137] neg_lo:[0,0,1] neg_hi:[0,0,1]
	v_pk_mul_f32 v[132:133], v[32:33], v[132:133]
	s_nop 0
	v_pk_fma_f32 v[132:133], v[40:41], v[180:181], v[132:133]
	s_cbranch_vccnz .LBB0_421
	s_and_saveexec_b64 s[12:13], s[10:11]
	s_cbranch_execz .LBB0_420
	v_readlane_b32 s48, v245, 25
	v_cndmask_b32_e64 v158, v173, v174, s[8:9]
	v_mov_b32_e32 v159, v147
	v_readlane_b32 s62, v245, 39
	v_readlane_b32 s63, v245, 40
	v_cndmask_b32_e64 v155, v155, v157, s[8:9]
	v_cndmask_b32_e64 v154, v154, v156, s[8:9]
	v_lshl_add_u64 v[158:159], s[62:63], 0, v[158:159]
	v_lshl_add_u64 v[154:155], v[158:159], 0, v[154:155]
	v_lshlrev_b32_e32 v156, 2, v176
	v_mov_b32_e32 v157, v147
	v_lshl_add_u64 v[154:155], v[154:155], 0, v[156:157]
	v_readlane_b32 s49, v245, 26
	v_readlane_b32 s50, v245, 27
	v_readlane_b32 s51, v245, 28
	v_readlane_b32 s52, v245, 29
	v_readlane_b32 s53, v245, 30
	v_readlane_b32 s54, v245, 31
	v_readlane_b32 s55, v245, 32
	v_readlane_b32 s56, v245, 33
	v_readlane_b32 s57, v245, 34
	v_readlane_b32 s58, v245, 35
	v_readlane_b32 s59, v245, 36
	v_readlane_b32 s60, v245, 37
	v_readlane_b32 s61, v245, 38
	global_store_dwordx4 v[154:155], v[134:137], off offset:512
	global_store_dwordx4 v[154:155], v[130:133], off offset:640

.LBB0_427:
	v_add_u32_e32 v160, 0xa0, v152
	s_movk_i32 s8, 0x3f60
	v_lshlrev_b32_e32 v130, 5, v160
	v_cmp_gt_i32_e64 s[8:9], s8, v152
	v_and_b32_e32 v130, 0xfde0, v130
	v_mov_b32_e32 v131, v147
	v_cndmask_b32_e64 v130, v172, v130, s[8:9]
	v_or_b32_e32 v130, v130, v165
	v_lshlrev_b32_e32 v158, 3, v130
	v_add_u32_e32 v130, 0xffffc0a0, v152
	v_lshlrev_b64 v[154:155], 11, v[130:131]
	v_mov_b32_e32 v178, v224
	v_mov_b32_e32 v179, v225
	v_mov_b32_e32 v180, v226
	v_mov_b32_e32 v181, v227
	v_mov_b32_e32 v130, v228
	v_mov_b32_e32 v131, v229
	v_mov_b32_e32 v132, v230
	v_mov_b32_e32 v133, v231
	s_movk_i32 s10, 0x3fe0
	v_ashrrev_i32_e32 v161, 31, v160
	v_cmp_gt_i32_e64 s[10:11], s10, v152
	v_lshlrev_b64 v[156:157], 11, v[160:161]
	s_mov_b64 s[12:13], -1
	s_and_b64 vcc, exec, s[4:5]
	v_mov_b32_e32 v137, v132
	v_mov_b32_e32 v132, v131
	v_mov_b32_e32 v136, v130
	v_pk_mul_f32 v[130:131], v[26:27], v[132:133]
	s_nop 0
	v_pk_fma_f32 v[134:135], v[34:35], v[136:137], v[130:131] neg_lo:[0,0,1] neg_hi:[0,0,1]
	v_pk_mul_f32 v[130:131], v[26:27], v[136:137]
	s_nop 0
	v_pk_fma_f32 v[130:131], v[34:35], v[132:133], v[130:131]
	v_mov_b32_e32 v133, v180
	v_mov_b32_e32 v180, v179
	v_mov_b32_e32 v132, v178
	v_pk_mul_f32 v[136:137], v[28:29], v[180:181]
	s_nop 0
	v_pk_fma_f32 v[136:137], v[36:37], v[132:133], v[136:137] neg_lo:[0,0,1] neg_hi:[0,0,1]
	v_pk_mul_f32 v[132:133], v[28:29], v[132:133]
	s_nop 0
	v_pk_fma_f32 v[132:133], v[36:37], v[180:181], v[132:133]
	s_cbranch_vccnz .LBB0_431
	s_and_saveexec_b64 s[12:13], s[10:11]
	s_cbranch_execz .LBB0_430
	v_readlane_b32 s48, v245, 25
	v_cndmask_b32_e64 v178, v173, v174, s[8:9]
	v_mov_b32_e32 v179, v147
	v_readlane_b32 s62, v245, 39
	v_readlane_b32 s63, v245, 40
	v_cndmask_b32_e64 v181, v155, v157, s[8:9]
	v_cndmask_b32_e64 v180, v154, v156, s[8:9]
	v_lshl_add_u64 v[178:179], s[62:63], 0, v[178:179]
	v_lshl_add_u64 v[178:179], v[178:179], 0, v[180:181]
	v_lshlrev_b32_e32 v180, 2, v176
	v_mov_b32_e32 v181, v147
	v_lshl_add_u64 v[178:179], v[178:179], 0, v[180:181]
	v_readlane_b32 s49, v245, 26
	v_readlane_b32 s50, v245, 27
	v_readlane_b32 s51, v245, 28
	v_readlane_b32 s52, v245, 29
	v_readlane_b32 s53, v245, 30
	v_readlane_b32 s54, v245, 31
	v_readlane_b32 s55, v245, 32
	v_readlane_b32 s56, v245, 33
	v_readlane_b32 s57, v245, 34
	v_readlane_b32 s58, v245, 35
	v_readlane_b32 s59, v245, 36
	v_readlane_b32 s60, v245, 37
	v_readlane_b32 s61, v245, 38
	global_store_dwordx4 v[178:179], v[134:137], off
	global_store_dwordx4 v[178:179], v[130:133], off offset:128

.LBB0_437:
	v_mov_b32_e32 v159, v147
	v_lshl_add_u64 v[130:131], s[44:45], 0, v[158:159]
	v_mov_b32_e32 v178, v224
	v_mov_b32_e32 v179, v225
	v_mov_b32_e32 v180, v226
	v_mov_b32_e32 v181, v227
	s_nop 0
	v_mov_b32_e32 v130, v228
	v_mov_b32_e32 v131, v229
	v_mov_b32_e32 v132, v230
	v_mov_b32_e32 v133, v231
	s_mov_b64 s[12:13], -1
	s_and_b64 vcc, exec, s[4:5]
	v_mov_b32_e32 v137, v132
	v_mov_b32_e32 v132, v131
	v_mov_b32_e32 v136, v130
	v_pk_mul_f32 v[130:131], v[14:15], v[132:133]
	s_nop 0
	v_pk_fma_f32 v[134:135], v[22:23], v[136:137], v[130:131] neg_lo:[0,0,1] neg_hi:[0,0,1]
	v_pk_mul_f32 v[130:131], v[14:15], v[136:137]
	s_nop 0
	v_pk_fma_f32 v[130:131], v[22:23], v[132:133], v[130:131]
	v_mov_b32_e32 v133, v180
	v_mov_b32_e32 v180, v179
	v_mov_b32_e32 v132, v178
	v_pk_mul_f32 v[136:137], v[16:17], v[180:181]
	s_nop 0
	v_pk_fma_f32 v[136:137], v[24:25], v[132:133], v[136:137] neg_lo:[0,0,1] neg_hi:[0,0,1]
	v_pk_mul_f32 v[132:133], v[16:17], v[132:133]
	s_nop 0
	v_pk_fma_f32 v[132:133], v[24:25], v[180:181], v[132:133]
	s_cbranch_vccnz .LBB0_441
	s_and_saveexec_b64 s[12:13], s[10:11]
	s_cbranch_execz .LBB0_440
	v_readlane_b32 s48, v245, 25
	v_cndmask_b32_e64 v158, v173, v174, s[8:9]
	v_mov_b32_e32 v159, v147
	v_readlane_b32 s62, v245, 39
	v_readlane_b32 s63, v245, 40
	v_cndmask_b32_e64 v155, v155, v157, s[8:9]
	v_cndmask_b32_e64 v154, v154, v156, s[8:9]
	v_lshl_add_u64 v[158:159], s[62:63], 0, v[158:159]
	v_lshl_add_u64 v[154:155], v[158:159], 0, v[154:155]
	v_lshlrev_b32_e32 v156, 2, v176
	v_mov_b32_e32 v157, v147
	v_lshl_add_u64 v[154:155], v[154:155], 0, v[156:157]
	v_readlane_b32 s49, v245, 26
	v_readlane_b32 s50, v245, 27
	v_readlane_b32 s51, v245, 28
	v_readlane_b32 s52, v245, 29
	v_readlane_b32 s53, v245, 30
	v_readlane_b32 s54, v245, 31
	v_readlane_b32 s55, v245, 32
	v_readlane_b32 s56, v245, 33
	v_readlane_b32 s57, v245, 34
	v_readlane_b32 s58, v245, 35
	v_readlane_b32 s59, v245, 36
	v_readlane_b32 s60, v245, 37
	v_readlane_b32 s61, v245, 38
	global_store_dwordx4 v[154:155], v[134:137], off offset:512
	global_store_dwordx4 v[154:155], v[130:133], off offset:640

.LBB0_447:
	v_add_u32_e32 v160, 0xb0, v152
	s_movk_i32 s8, 0x3f50
	v_lshlrev_b32_e32 v130, 5, v160
	v_cmp_gt_i32_e64 s[8:9], s8, v152
	v_and_b32_e32 v130, 0xffe0, v130
	v_mov_b32_e32 v131, v147
	v_cndmask_b32_e64 v130, v172, v130, s[8:9]
	v_or_b32_e32 v130, v130, v165
	v_lshlrev_b32_e32 v158, 3, v130
	v_add_u32_e32 v130, 0xffffc0b0, v152
	v_lshlrev_b64 v[154:155], 11, v[130:131]
	v_mov_b32_e32 v178, v232
	v_mov_b32_e32 v179, v233
	v_mov_b32_e32 v180, v234
	v_mov_b32_e32 v181, v235
	v_mov_b32_e32 v130, v236
	v_mov_b32_e32 v131, v237
	v_mov_b32_e32 v132, v238
	v_mov_b32_e32 v133, v239
	s_movk_i32 s10, 0x3fd0
	v_ashrrev_i32_e32 v161, 31, v160
	v_cmp_gt_i32_e64 s[10:11], s10, v152
	v_lshlrev_b64 v[156:157], 11, v[160:161]
	s_mov_b64 s[12:13], -1
	s_and_b64 vcc, exec, s[4:5]
	v_mov_b32_e32 v137, v132
	v_mov_b32_e32 v132, v131
	v_mov_b32_e32 v136, v130
	v_pk_mul_f32 v[130:131], v[10:11], v[132:133]
	s_nop 0
	v_pk_fma_f32 v[134:135], v[18:19], v[136:137], v[130:131] neg_lo:[0,0,1] neg_hi:[0,0,1]
	v_pk_mul_f32 v[130:131], v[10:11], v[136:137]
	s_nop 0
	v_pk_fma_f32 v[130:131], v[18:19], v[132:133], v[130:131]
	v_mov_b32_e32 v133, v180
	v_mov_b32_e32 v180, v179
	v_mov_b32_e32 v132, v178
	v_pk_mul_f32 v[136:137], v[12:13], v[180:181]
	s_nop 0
	v_pk_fma_f32 v[136:137], v[20:21], v[132:133], v[136:137] neg_lo:[0,0,1] neg_hi:[0,0,1]
	v_pk_mul_f32 v[132:133], v[12:13], v[132:133]
	s_nop 0
	v_pk_fma_f32 v[132:133], v[20:21], v[180:181], v[132:133]
	s_cbranch_vccnz .LBB0_451
	s_and_saveexec_b64 s[12:13], s[10:11]
	s_cbranch_execz .LBB0_450
	v_readlane_b32 s48, v245, 25
	v_cndmask_b32_e64 v178, v173, v174, s[8:9]
	v_mov_b32_e32 v179, v147
	v_readlane_b32 s62, v245, 39
	v_readlane_b32 s63, v245, 40
	v_cndmask_b32_e64 v181, v155, v157, s[8:9]
	v_cndmask_b32_e64 v180, v154, v156, s[8:9]
	v_lshl_add_u64 v[178:179], s[62:63], 0, v[178:179]
	v_lshl_add_u64 v[178:179], v[178:179], 0, v[180:181]
	v_lshlrev_b32_e32 v180, 2, v176
	v_mov_b32_e32 v181, v147
	v_lshl_add_u64 v[178:179], v[178:179], 0, v[180:181]
	v_readlane_b32 s49, v245, 26
	v_readlane_b32 s50, v245, 27
	v_readlane_b32 s51, v245, 28
	v_readlane_b32 s52, v245, 29
	v_readlane_b32 s53, v245, 30
	v_readlane_b32 s54, v245, 31
	v_readlane_b32 s55, v245, 32
	v_readlane_b32 s56, v245, 33
	v_readlane_b32 s57, v245, 34
	v_readlane_b32 s58, v245, 35
	v_readlane_b32 s59, v245, 36
	v_readlane_b32 s60, v245, 37
	v_readlane_b32 s61, v245, 38
	global_store_dwordx4 v[178:179], v[134:137], off
	global_store_dwordx4 v[178:179], v[130:133], off offset:128

.LBB0_457:
	v_mov_b32_e32 v159, v147
	v_lshl_add_u64 v[134:135], s[44:45], 0, v[158:159]
	v_mov_b32_e32 v130, v236
	v_mov_b32_e32 v131, v237
	v_mov_b32_e32 v132, v238
	v_mov_b32_e32 v133, v239
	v_mov_b32_e32 v178, v232
	v_mov_b32_e32 v179, v233
	v_mov_b32_e32 v180, v234
	v_mov_b32_e32 v181, v235
	s_and_b64 vcc, exec, s[4:5]
	s_mov_b64 s[4:5], -1
	v_mov_b32_e32 v134, v130
	v_mov_b32_e32 v135, v132
	v_mov_b32_e32 v132, v131
	v_mov_b32_e32 v136, v178
	v_mov_b32_e32 v137, v180
	v_mov_b32_e32 v180, v179
	v_pk_mul_f32 v[130:131], v[2:3], v[132:133]
	v_pk_mul_f32 v[158:159], v[2:3], v[134:135]
	v_pk_mul_f32 v[178:179], v[4:5], v[180:181]
	v_pk_mul_f32 v[182:183], v[4:5], v[136:137]
	v_pk_fma_f32 v[134:135], v[6:7], v[134:135], v[130:131] neg_lo:[0,0,1] neg_hi:[0,0,1]
	v_pk_fma_f32 v[130:131], v[6:7], v[132:133], v[158:159]
	v_pk_fma_f32 v[136:137], v[8:9], v[136:137], v[178:179] neg_lo:[0,0,1] neg_hi:[0,0,1]
	v_pk_fma_f32 v[132:133], v[8:9], v[180:181], v[182:183]
	s_cbranch_vccnz .LBB0_461
	s_and_saveexec_b64 s[4:5], s[10:11]
	s_cbranch_execz .LBB0_460
	v_readlane_b32 s48, v245, 25
	v_cndmask_b32_e64 v146, v173, v174, s[8:9]
	v_readlane_b32 s62, v245, 39
	v_readlane_b32 s63, v245, 40
	v_cndmask_b32_e64 v155, v155, v157, s[8:9]
	v_cndmask_b32_e64 v154, v154, v156, s[8:9]
	v_lshl_add_u64 v[158:159], s[62:63], 0, v[146:147]
	v_lshl_add_u64 v[154:155], v[158:159], 0, v[154:155]
	v_lshlrev_b32_e32 v146, 2, v176
	v_lshl_add_u64 v[154:155], v[154:155], 0, v[146:147]
	v_readlane_b32 s49, v245, 26
	v_readlane_b32 s50, v245, 27
	v_readlane_b32 s51, v245, 28
	v_readlane_b32 s52, v245, 29
	v_readlane_b32 s53, v245, 30
	v_readlane_b32 s54, v245, 31
	v_readlane_b32 s55, v245, 32
	v_readlane_b32 s56, v245, 33
	v_readlane_b32 s57, v245, 34
	v_readlane_b32 s58, v245, 35
	v_readlane_b32 s59, v245, 36
	v_readlane_b32 s60, v245, 37
	v_readlane_b32 s61, v245, 38
	global_store_dwordx4 v[154:155], v[134:137], off offset:512
	global_store_dwordx4 v[154:155], v[130:133], off offset:640
